# attention: static s_setprio 1 for waves 4-7 during the phase; removed NaN-canonicalizing self-max ops from the row-max chain (same result for non-NaN)
# speedup vs baseline: 1.0069x; 1.0021x over previous
; __device__ __forceinline__ CArgs* kargs() { CArgs* p = (CArgs*)__builtin_amdgcn_kernarg_segment_ptr(); asm volatile("" : "+s"(p)); return p; }
;   const int nx=(G%8==0)?8:1, per=G/nx, x=vcu/per, c=vcu%per, gpx=(BATCH*NKVH)/nx;
;   for(int gi=x*gpx;gi<(x+1)*gpx;++gi){
;     const int b=gi/NKVH,kvh=gi%NKVH;
;     for(int u=c;u<(NHEAD/NKVH)*NQB;u+=per){ const int h=kvh*(NHEAD/NKVH)+u/NQB, qb=u%NQB; attn_unit<THRL>(b,h,qb,T.Q,T.K,T.V,T.O,lds); }
; __global__ void __launch_bounds__(NTHREADS, 2) fwd_mega(Args a_unused) {
;     ...
;                     {   CArgs* A = kargs(); unsigned char* ws = A->ws; const bf16_t* RA = (const bf16_t*)(ws + WS_A);
;                         const attn_body::AttnTensors AT{(const attn_body::bf16*)RA, (const attn_body::bf16*)(RA + 1024), (const attn_body::bf16*)(RA + 1280), (attn_body::bf16*)(ws + WS_B)};
;     ...
;                         attn_body::attn_phase<8>((char*)lds_raw, AT, VCU(), (int)gridDim.x);
.LBB0_771:
	s_or_b64 exec, exec, s[6:7]
	v_readlane_b32 s4, v254, 45
	v_readlane_b32 s5, v254, 46
	s_mov_b64 s[6:7], s[0:1]
	s_andn2_b64 vcc, exec, s[4:5]
	s_waitcnt lgkmcnt(0)
	s_barrier
	s_cbranch_vccnz .LBB0_827
	v_readfirstlane_b32 s4, v228
	s_cmpk_lt_u32 s4, 0x100
	s_cbranch_scc1 .Lattn_prio_done
	s_setprio 1
.Lattn_prio_done:
	s_load_dwordx2 s[6:7], s[6:7], 0xd8
	v_readlane_b32 s76, v254, 44
	s_waitcnt lgkmcnt(0)
	s_add_u32 s4, s6, 0x12800000
	s_addc_u32 s5, s7, 0
	s_add_u32 s36, s6, 0x12800800
	s_addc_u32 s37, s7, 0
	s_add_u32 s46, s6, 0x12800a00
	s_addc_u32 s47, s7, 0
	s_add_u32 s54, s6, 0x2a800000
	s_addc_u32 s55, s7, 0
	s_add_u32 s56, s6, 0x12830800
	s_addc_u32 s57, s7, 0
	s_add_u32 s58, s6, 0x12830a00
	s_addc_u32 s59, s7, 0
	s_add_u32 s60, s6, 0x13310800
	s_addc_u32 s61, s7, 0
	s_branch .LBB0_774

.LBB0_778:
	v_add_u32_e32 v214, s22, v209
	ds_read_b64_tr_b16 v[176:177], v214 offset:24576
	ds_read_b64_tr_b16 v[178:179], v214 offset:25088
	s_waitcnt lgkmcnt(9)
	v_mfma_f32_32x32x16_bf16 v[96:111], v[172:175], v[140:143], v[32:47]
	v_add_f32_e32 v80, v64, v65
	v_add_f32_e32 v80, v66, v80
	v_add_f32_e32 v80, v67, v80
	v_add_f32_e32 v80, v68, v80
	v_add_f32_e32 v80, v69, v80
	v_cvt_pk_bf16_f32 v132, v64, v65
	v_cvt_pk_bf16_f32 v133, v66, v67
	ds_read_b64_tr_b16 v[172:173], v214 offset:28672
	ds_read_b64_tr_b16 v[174:175], v214 offset:29184
	v_add_f32_e32 v64, v70, v80
	s_waitcnt lgkmcnt(10)
	v_mfma_f32_32x32x16_bf16 v[80:95], v[168:171], v[140:143], v[32:47]
	v_add_f32_e32 v64, v71, v64
	v_add_f32_e32 v64, v72, v64
	v_add_f32_e32 v112, v73, v64
	v_cvt_pk_bf16_f32 v134, v68, v69
	v_cvt_pk_bf16_f32 v135, v70, v71
	ds_read_b64_tr_b16 v[64:65], v214 offset:25600
	ds_read_b64_tr_b16 v[66:67], v214 offset:26112
	s_waitcnt lgkmcnt(11)
	v_mfma_f32_32x32x16_bf16 v[96:111], v[164:167], v[136:139], v[96:111]
	v_add_f32_e32 v68, v74, v112
	v_add_f32_e32 v68, v75, v68
	v_add_f32_e32 v68, v76, v68
	v_add_f32_e32 v112, v77, v68
	v_cvt_pk_bf16_f32 v124, v72, v73
	v_cvt_pk_bf16_f32 v125, v74, v75
	ds_read_b64_tr_b16 v[68:69], v214 offset:29696
	ds_read_b64_tr_b16 v[70:71], v214 offset:30208
	s_waitcnt lgkmcnt(12)
	v_mfma_f32_32x32x16_bf16 v[80:95], v[160:163], v[136:139], v[80:95]
	v_add_f32_e32 v72, v78, v112
	v_add_f32_e32 v72, v79, v72
	v_add_f32_e32 v72, v48, v72
	v_add_f32_e32 v112, v49, v72
	v_cvt_pk_bf16_f32 v126, v76, v77
	v_cvt_pk_bf16_f32 v127, v78, v79
	ds_read_b64_tr_b16 v[72:73], v214 offset:26624
	ds_read_b64_tr_b16 v[74:75], v214 offset:27136
	s_waitcnt lgkmcnt(13)
	v_mfma_f32_32x32x16_bf16 v[96:111], v[156:159], v[128:131], v[96:111]
	v_add_f32_e32 v76, v50, v112
	v_add_f32_e32 v76, v51, v76
	v_add_f32_e32 v76, v52, v76
	v_add_f32_e32 v76, v53, v76
	v_cvt_pk_bf16_f32 v116, v48, v49
	v_cvt_pk_bf16_f32 v117, v50, v51
	ds_read_b64_tr_b16 v[48:49], v214 offset:30720
	ds_read_b64_tr_b16 v[50:51], v214 offset:31232
	s_waitcnt lgkmcnt(14)
	v_mfma_f32_32x32x16_bf16 v[80:95], v[152:155], v[128:131], v[80:95]
	v_add_f32_e32 v76, v54, v76
	v_add_f32_e32 v76, v55, v76
	v_add_f32_e32 v76, v56, v76
	v_add_f32_e32 v76, v57, v76
	v_cvt_pk_bf16_f32 v118, v52, v53
	v_cvt_pk_bf16_f32 v119, v54, v55
	ds_read_b64_tr_b16 v[52:53], v214 offset:27648
	ds_read_b64_tr_b16 v[54:55], v214 offset:28160
	s_waitcnt lgkmcnt(14)
	v_mfma_f32_32x32x16_bf16 v[96:111], v[148:151], v[120:123], v[96:111]
	v_add_f32_e32 v76, v58, v76
	v_add_f32_e32 v76, v59, v76
	v_add_f32_e32 v76, v60, v76
	v_add_f32_e32 v76, v61, v76
	v_cvt_pk_bf16_f32 v112, v56, v57
	v_cvt_pk_bf16_f32 v113, v58, v59
	ds_read_b64_tr_b16 v[56:57], v214 offset:31744
	ds_read_b64_tr_b16 v[58:59], v214 offset:32256
	v_mfma_f32_32x32x16_bf16 v[80:95], v[144:147], v[120:123], v[80:95]
	v_add_f32_e32 v76, v62, v76
	v_add_f32_e32 v76, v63, v76
	v_add_f32_e32 v76, 0, v76
	v_cvt_pk_bf16_f32 v114, v60, v61
	v_cvt_pk_bf16_f32 v115, v62, v63
	v_lshl_add_u64 v[60:61], v[192:193], 0, s[86:87]
	s_add_i32 s22, s3, s38
	s_mov_b32 s23, m0
	s_mov_b32 m0, s22
	s_nop 0
	global_load_lds_dwordx4 v[60:61], off
	s_mov_b32 m0, s23
	v_lshl_add_u64 v[60:61], v[194:195], 0, s[82:83]
	s_add_i32 s22, s53, s39
	s_mov_b32 s23, m0
	s_mov_b32 m0, s22
	s_nop 0
	global_load_lds_dwordx4 v[60:61], off
	s_mov_b32 m0, s23
	v_max_f32_e32 v60, v96, v97
	v_max3_f32 v61, v98, v99, v81
	v_max3_f32 v60, v60, v80, v82
	v_max3_f32 v60, v60, v83, v100
	v_max3_f32 v61, v61, v102, v103
	v_max3_f32 v60, v60, v101, v84
	v_max3_f32 v61, v61, v86, v87
	v_max3_f32 v60, v60, v85, v104
	v_max3_f32 v61, v61, v106, v107
	v_max3_f32 v60, v60, v105, v88
	v_max3_f32 v61, v61, v90, v91
	v_max3_f32 v60, v60, v89, v108
	v_max3_f32 v61, v61, v110, v111
	v_max3_f32 v60, v60, v109, v92
	v_max3_f32 v61, v61, v94, v95
	v_max3_f32 v60, v60, v93, v61
	v_mov_b32_e32 v61, v60
	s_nop 1
	v_permlane32_swap_b32_e32 v60, v61
	v_max_f32_e32 v60, v60, v61
	v_cmp_lt_f32_e32 vcc, s12, v60
	s_cmp_lg_u64 vcc, 0
	v_add_f32_e32 v180, v180, v76
	s_cselect_b64 s[42:43], -1, 0
	s_cbranch_vccnz .LBB0_786

.LBB0_781:
	s_add_i32 s22, s53, 0x2000
	s_cmpk_lg_i32 s53, 0x4000
	s_cselect_b32 s44, s22, 0
	v_add_u32_e32 v214, s3, v209
	ds_read_b64_tr_b16 v[148:149], v214 offset:24576
	ds_read_b64_tr_b16 v[150:151], v214 offset:25088
	s_waitcnt lgkmcnt(9)
	v_mfma_f32_32x32x16_bf16 v[64:79], v[60:63], v[140:143], v[32:47]
	v_add_f32_e32 v48, v96, v97
	v_add_f32_e32 v48, v98, v48
	v_add_f32_e32 v48, v99, v48
	v_add_f32_e32 v48, v100, v48
	v_add_f32_e32 v48, v101, v48
	v_cvt_pk_bf16_f32 v132, v96, v97
	v_cvt_pk_bf16_f32 v133, v98, v99
	ds_read_b64_tr_b16 v[144:145], v214 offset:28672
	ds_read_b64_tr_b16 v[146:147], v214 offset:29184
	v_add_f32_e32 v48, v102, v48
	v_add_f32_e32 v48, v103, v48
	v_add_f32_e32 v48, v104, v48
	v_add_f32_e32 v112, v105, v48
	s_waitcnt lgkmcnt(10)
	v_mfma_f32_32x32x16_bf16 v[48:63], v[172:175], v[140:143], v[32:47]
	v_cvt_pk_bf16_f32 v134, v100, v101
	v_cvt_pk_bf16_f32 v135, v102, v103
	ds_read_b64_tr_b16 v[96:97], v214 offset:25600
	ds_read_b64_tr_b16 v[98:99], v214 offset:26112
	s_waitcnt lgkmcnt(11)
	v_mfma_f32_32x32x16_bf16 v[64:79], v[176:179], v[136:139], v[64:79]
	v_add_f32_e32 v100, v106, v112
	v_add_f32_e32 v100, v107, v100
	v_add_f32_e32 v100, v108, v100
	v_add_f32_e32 v112, v109, v100
	v_cvt_pk_bf16_f32 v124, v104, v105
	v_cvt_pk_bf16_f32 v125, v106, v107
	ds_read_b64_tr_b16 v[100:101], v214 offset:29696
	ds_read_b64_tr_b16 v[102:103], v214 offset:30208
	s_waitcnt lgkmcnt(12)
	v_mfma_f32_32x32x16_bf16 v[48:63], v[168:171], v[136:139], v[48:63]
	v_add_f32_e32 v104, v110, v112
	v_add_f32_e32 v104, v111, v104
	v_add_f32_e32 v104, v80, v104
	v_add_f32_e32 v112, v81, v104
	v_cvt_pk_bf16_f32 v126, v108, v109
	v_cvt_pk_bf16_f32 v127, v110, v111
	ds_read_b64_tr_b16 v[104:105], v214 offset:26624
	ds_read_b64_tr_b16 v[106:107], v214 offset:27136
	s_waitcnt lgkmcnt(13)
	v_mfma_f32_32x32x16_bf16 v[64:79], v[164:167], v[128:131], v[64:79]
	v_add_f32_e32 v108, v82, v112
	v_add_f32_e32 v108, v83, v108
	v_add_f32_e32 v108, v84, v108
	v_add_f32_e32 v108, v85, v108
	v_cvt_pk_bf16_f32 v116, v80, v81
	v_cvt_pk_bf16_f32 v117, v82, v83
	ds_read_b64_tr_b16 v[80:81], v214 offset:30720
	ds_read_b64_tr_b16 v[82:83], v214 offset:31232
	s_waitcnt lgkmcnt(14)
	v_mfma_f32_32x32x16_bf16 v[48:63], v[160:163], v[128:131], v[48:63]
	v_add_f32_e32 v108, v86, v108
	v_add_f32_e32 v108, v87, v108
	v_add_f32_e32 v108, v88, v108
	v_add_f32_e32 v108, v89, v108
	v_cvt_pk_bf16_f32 v118, v84, v85
	v_cvt_pk_bf16_f32 v119, v86, v87
	ds_read_b64_tr_b16 v[84:85], v214 offset:27648
	ds_read_b64_tr_b16 v[86:87], v214 offset:28160
	s_waitcnt lgkmcnt(14)
	v_mfma_f32_32x32x16_bf16 v[64:79], v[156:159], v[120:123], v[64:79]
	v_add_f32_e32 v108, v90, v108
	v_add_f32_e32 v108, v91, v108
	v_add_f32_e32 v108, v92, v108
	v_add_f32_e32 v108, v93, v108
	v_cvt_pk_bf16_f32 v112, v88, v89
	v_cvt_pk_bf16_f32 v113, v90, v91
	ds_read_b64_tr_b16 v[88:89], v214 offset:31744
	ds_read_b64_tr_b16 v[90:91], v214 offset:32256
	v_mfma_f32_32x32x16_bf16 v[48:63], v[152:155], v[120:123], v[48:63]
	v_add_f32_e32 v108, v94, v108
	v_add_f32_e32 v108, v95, v108
	v_add_f32_e32 v108, 0, v108
	v_cvt_pk_bf16_f32 v114, v92, v93
	v_cvt_pk_bf16_f32 v115, v94, v95
	v_lshl_add_u64 v[92:93], v[192:193], 0, s[88:89]
	s_add_i32 s3, s53, s38
	s_mov_b32 s22, m0
	s_mov_b32 m0, s3
	s_nop 0
	global_load_lds_dwordx4 v[92:93], off
	s_mov_b32 m0, s22
	v_max_f32_e32 v92, v64, v65
	s_nop 1
	v_max3_f32 v93, v66, v67, v49
	v_max3_f32 v92, v92, v48, v50
	v_max3_f32 v92, v92, v51, v68
	v_max3_f32 v93, v93, v70, v71
	v_max3_f32 v92, v92, v69, v52
	v_max3_f32 v93, v93, v54, v55
	v_max3_f32 v92, v92, v53, v72
	v_max3_f32 v93, v93, v74, v75
	v_max3_f32 v92, v92, v73, v56
	v_max3_f32 v93, v93, v58, v59
	v_max3_f32 v92, v92, v57, v76
	v_max3_f32 v93, v93, v78, v79
	v_max3_f32 v92, v92, v77, v60
	v_max3_f32 v93, v93, v62, v63
	v_max3_f32 v92, v92, v61, v93
	v_mov_b32_e32 v93, v92
	s_nop 1
	v_permlane32_swap_b32_e32 v92, v93
	v_max_f32_e32 v92, v92, v93
	v_lshl_add_u64 v[194:195], v[194:195], 0, s[84:85]
	s_add_i32 s3, s44, s39
	s_mov_b32 s22, m0
	s_mov_b32 m0, s3
	s_nop 0
	global_load_lds_dwordx4 v[194:195], off
	s_mov_b32 m0, s22
	v_cmp_lt_f32_e32 vcc, s12, v92
	s_cmp_lg_u64 vcc, 0
	v_add_f32_e32 v180, v180, v108
	s_cselect_b64 s[42:43], -1, 0
	s_cbranch_vccnz .LBB0_789

.LBB0_795:
	v_lshl_add_u64 v[192:193], s[50:51], 1, v[188:189]
	v_lshl_add_u64 v[60:61], v[192:193], 0, s[82:83]
	s_add_i32 s22, s73, s39
	s_mov_b32 s23, m0
	s_mov_b32 m0, s22
	s_nop 0
	global_load_lds_dwordx4 v[60:61], off
	s_mov_b32 m0, s23
	v_max_f32_e32 v60, v96, v97
	v_max3_f32 v61, v98, v99, v81
	v_max3_f32 v60, v60, v80, v82
	v_max3_f32 v60, v60, v83, v100
	v_max3_f32 v61, v61, v102, v103
	v_max3_f32 v60, v60, v101, v84
	v_max3_f32 v61, v61, v86, v87
	v_max3_f32 v60, v60, v85, v104
	v_max3_f32 v61, v61, v106, v107
	v_max3_f32 v60, v60, v105, v88
	v_max3_f32 v61, v61, v90, v91
	v_max3_f32 v60, v60, v89, v108
	v_max3_f32 v61, v61, v110, v111
	v_max3_f32 v60, v60, v109, v92
	v_max3_f32 v61, v61, v94, v95
	v_max3_f32 v60, v60, v93, v61
	v_mov_b32_e32 v61, v60
	s_nop 1
	v_permlane32_swap_b32_e32 v60, v61
	v_max_f32_e32 v60, v60, v61
	v_cmp_lt_f32_e32 vcc, s12, v60
	s_cmp_lg_u64 vcc, 0
	v_add_f32_e32 v180, v180, v76
	s_cselect_b64 s[52:53], -1, 0
	s_cbranch_vccnz .LBB0_813

.LBB0_802:
	s_add_i32 s22, s73, 0x2000
	s_cmpk_lg_i32 s73, 0x4000
	s_cselect_b32 s62, s22, 0
	v_lshl_add_u64 v[92:93], v[192:193], 0, s[84:85]
	s_add_i32 s22, s62, s39
	s_mov_b32 s23, m0
	s_mov_b32 m0, s22
	s_nop 0
	global_load_lds_dwordx4 v[92:93], off
	s_mov_b32 m0, s23
	v_max_f32_e32 v92, v64, v65
	v_max3_f32 v93, v66, v67, v49
	v_max3_f32 v92, v92, v48, v50
	v_max3_f32 v92, v92, v51, v68
	v_max3_f32 v93, v93, v70, v71
	v_max3_f32 v92, v92, v69, v52
	v_max3_f32 v93, v93, v54, v55
	v_max3_f32 v92, v92, v53, v72
	v_max3_f32 v93, v93, v74, v75
	v_max3_f32 v92, v92, v73, v56
	v_max3_f32 v93, v93, v58, v59
	v_max3_f32 v92, v92, v57, v76
	v_max3_f32 v93, v93, v78, v79
	v_max3_f32 v92, v92, v77, v60
	v_max3_f32 v93, v93, v62, v63
	v_max3_f32 v92, v92, v61, v93
	v_mov_b32_e32 v93, v92
	s_nop 1
	v_permlane32_swap_b32_e32 v92, v93
	v_max_f32_e32 v92, v92, v93
	v_cmp_lt_f32_e32 vcc, s12, v92
	s_cmp_lg_u64 vcc, 0
	v_add_f32_e32 v180, v180, v108
	s_cselect_b64 s[50:51], -1, 0
	s_cbranch_vccnz .LBB0_816

;   #define RESC() do{ if(resc){ asm volatile("s_waitcnt lgkmcnt(0)":::"memory"); \
;       _Pragma("unroll") for(int d_=0;d_<2;++d_) _Pragma("unroll") for(int r=0;r<16;++r)o[d_][r]*=wsf[crow(r,hi)]; } }while(0)
; template<int THRL> __device__ __forceinline__ void attn_unit(int b,int h,int qb,const bf16*Q,const bf16*__restrict__ K,const bf16*__restrict__ V,bf16*O,char*shm){
;     ...
;   STEP(pB0,pB1,pA0,pA1,NT-1,false,false,false); RESC();
.LBB0_819:
	ds_read_b64_tr_b16 v[96:97], v209 offset:40960
	ds_read_b64_tr_b16 v[98:99], v209 offset:41472
	v_add_f32_e32 v80, v64, v65
	v_add_f32_e32 v80, v66, v80
	v_add_f32_e32 v80, v67, v80
	v_add_f32_e32 v80, v68, v80
	v_add_f32_e32 v100, v69, v80
	s_waitcnt lgkmcnt(9)
	v_mfma_f32_32x32x16_bf16 v[80:95], v[172:175], v[140:143], v[32:47]
	v_cvt_pk_bf16_f32 v132, v64, v65
	v_cvt_pk_bf16_f32 v133, v66, v67
	ds_read_b64_tr_b16 v[64:65], v209 offset:45056
	ds_read_b64_tr_b16 v[66:67], v209 offset:45568
	s_waitcnt lgkmcnt(10)
	v_mfma_f32_32x32x16_bf16 v[32:47], v[168:171], v[140:143], v[32:47]
	v_add_f32_e32 v100, v70, v100
	v_add_f32_e32 v100, v71, v100
	v_add_f32_e32 v100, v72, v100
	v_add_f32_e32 v100, v73, v100
	v_cvt_pk_bf16_f32 v134, v68, v69
	v_cvt_pk_bf16_f32 v135, v70, v71
	ds_read_b64_tr_b16 v[68:69], v209 offset:41984
	ds_read_b64_tr_b16 v[70:71], v209 offset:42496
	s_waitcnt lgkmcnt(11)
	v_mfma_f32_32x32x16_bf16 v[80:95], v[164:167], v[136:139], v[80:95]
	v_add_f32_e32 v100, v74, v100
	v_add_f32_e32 v100, v75, v100
	v_add_f32_e32 v100, v76, v100
	v_add_f32_e32 v100, v77, v100
	v_cvt_pk_bf16_f32 v124, v72, v73
	v_cvt_pk_bf16_f32 v125, v74, v75
	ds_read_b64_tr_b16 v[72:73], v209 offset:46080
	ds_read_b64_tr_b16 v[74:75], v209 offset:46592
	s_waitcnt lgkmcnt(12)
	v_mfma_f32_32x32x16_bf16 v[32:47], v[160:163], v[136:139], v[32:47]
	v_add_f32_e32 v100, v78, v100
	v_add_f32_e32 v100, v79, v100
	v_add_f32_e32 v100, v48, v100
	v_add_f32_e32 v100, v49, v100
	v_cvt_pk_bf16_f32 v126, v76, v77
	v_cvt_pk_bf16_f32 v127, v78, v79
	ds_read_b64_tr_b16 v[76:77], v209 offset:43008
	ds_read_b64_tr_b16 v[78:79], v209 offset:43520
	s_waitcnt lgkmcnt(13)
	v_mfma_f32_32x32x16_bf16 v[80:95], v[156:159], v[128:131], v[80:95]
	v_add_f32_e32 v100, v50, v100
	v_add_f32_e32 v100, v51, v100
	v_add_f32_e32 v100, v52, v100
	v_add_f32_e32 v104, v53, v100
	v_cvt_pk_bf16_f32 v116, v48, v49
	v_cvt_pk_bf16_f32 v117, v50, v51
	ds_read_b64_tr_b16 v[100:101], v209 offset:47104
	ds_read_b64_tr_b16 v[102:103], v209 offset:47616
	s_waitcnt lgkmcnt(14)
	v_mfma_f32_32x32x16_bf16 v[32:47], v[152:155], v[128:131], v[32:47]
	v_add_f32_e32 v48, v54, v104
	v_add_f32_e32 v48, v55, v48
	v_add_f32_e32 v48, v56, v48
	v_add_f32_e32 v48, v57, v48
	v_cvt_pk_bf16_f32 v118, v52, v53
	v_cvt_pk_bf16_f32 v119, v54, v55
	ds_read_b64_tr_b16 v[104:105], v209 offset:44032
	ds_read_b64_tr_b16 v[106:107], v209 offset:44544
	s_waitcnt lgkmcnt(14)
	v_mfma_f32_32x32x16_bf16 v[80:95], v[148:151], v[120:123], v[80:95]
	v_add_f32_e32 v48, v58, v48
	v_add_f32_e32 v48, v59, v48
	v_add_f32_e32 v48, v60, v48
	v_add_f32_e32 v48, v61, v48
	v_cvt_pk_bf16_f32 v112, v56, v57
	v_cvt_pk_bf16_f32 v113, v58, v59
	ds_read_b64_tr_b16 v[108:109], v209 offset:48128
	ds_read_b64_tr_b16 v[110:111], v209 offset:48640
	v_mfma_f32_32x32x16_bf16 v[32:47], v[144:147], v[120:123], v[32:47]
	v_add_f32_e32 v48, v62, v48
	v_add_f32_e32 v48, v63, v48
	v_add_f32_e32 v48, 0, v48
	v_cvt_pk_bf16_f32 v114, v60, v61
	v_cvt_pk_bf16_f32 v115, v62, v63
	v_max_f32_e32 v49, v80, v81
	s_nop 3
	v_max3_f32 v50, v82, v83, v33
	v_max3_f32 v49, v49, v32, v34
	v_max3_f32 v49, v49, v35, v84
	v_max3_f32 v50, v50, v86, v87
	v_max3_f32 v49, v49, v85, v36
	v_max3_f32 v50, v50, v38, v39
	v_max3_f32 v49, v49, v37, v88
	v_max3_f32 v50, v50, v90, v91
	v_max3_f32 v49, v49, v89, v40
	v_max3_f32 v50, v50, v42, v43
	v_max3_f32 v49, v49, v41, v92
	v_max3_f32 v50, v50, v94, v95
	v_max3_f32 v49, v49, v93, v44
	v_max3_f32 v50, v50, v46, v47
	v_add_f32_e32 v120, v180, v48
	v_max3_f32 v48, v49, v45, v50
	v_mov_b32_e32 v49, v48
	s_nop 1
	v_permlane32_swap_b32_e32 v48, v49
	v_max_f32_e32 v48, v48, v49
	v_cmp_lt_f32_e32 vcc, s12, v48
	s_cmp_lg_u64 vcc, 0
	s_cselect_b64 s[42:43], -1, 0
	s_cbranch_vccnz .LBB0_824

; __device__ __forceinline__ unsigned xb_ld(unsigned* p)              { return __hip_atomic_load(p, __ATOMIC_RELAXED, __HIP_MEMORY_SCOPE_AGENT); }
; __device__ __forceinline__ void xcd_barrier_complete(unsigned* bar, unsigned x, unsigned& nloc, unsigned& nx) {
;     const unsigned G = gridDim.x * gridDim.y * gridDim.z;
;     unsigned sum, cnt, mine, sp = 0u;
;     for (;;) {
;         sum = 0u; cnt = 0u; mine = 0u;
; #pragma unroll
;         for (unsigned j = 0; j < 16; ++j) { const unsigned c = xb_ld(&bar[XB_XCNT(j)]); sum += c; cnt += (c > 0u) ? 1u : 0u; mine = (j == x) ? c : mine; }
;         if (sum == G) break;
;         __builtin_amdgcn_s_sleep(1);
;         if ((++sp & 255u) == 0u) { if (xb_ld(&bar[XB_TMO])) break; if (sp > XB_SPIN_CAP) { atomicAdd(&bar[XB_TMO], 1u); break; } }
;     }
;     nloc = mine > 0u ? mine : 1u; nx = cnt > 0u ? cnt : 1u;
; }
; __device__ __forceinline__ void xcd_barrier(const XcdBarrier& b) {
;     asm volatile("s_waitcnt vmcnt(0)" ::: "memory");
;     __syncthreads();
;     if (threadIdx.x == 0) {
;         unsigned* bar = b.bar;
;         __builtin_amdgcn_s_waitcnt(0);
;         unsigned nloc = b.st[0], nx = b.st[1];
;         if (nloc == 0u) { xcd_barrier_complete(bar, b.x, nloc, nx); b.st[0] = nloc; b.st[1] = nx; }
.LBB0_827:
	s_setprio 0
	s_mov_b64 s[8:9], s[0:1]
	s_getreg_b32 s3, hwreg(HW_REG_XCC_ID, 0, 4)
	s_waitcnt vmcnt(0)
	s_barrier
	s_mov_b64 s[6:7], exec
	v_readlane_b32 s4, v254, 0
	v_readlane_b32 s5, v254, 1
	s_and_b64 s[4:5], s[6:7], s[4:5]
	s_mov_b64 exec, s[4:5]
	s_cbranch_execz .LBB0_879
	v_readlane_b32 s4, v254, 55
	s_load_dwordx2 s[8:9], s[8:9], 0xd8
	s_waitcnt vmcnt(0) expcnt(0) lgkmcnt(0)
	v_mov_b32_e32 v0, s4
	ds_read_b32 v2, v0
	v_readlane_b32 s4, v254, 56
	s_and_b32 s3, s3, 15
	s_waitcnt lgkmcnt(0)
	v_cmp_ne_u32_e32 vcc, 0, v2
	v_mov_b32_e32 v0, s4
	ds_read_b32 v0, v0
	s_cbranch_vccnz .LBB0_843
	s_add_u32 s10, s8, 0x3a800200
	s_addc_u32 s11, s9, 0
	s_add_u32 s14, s8, 0x3a800400
	s_addc_u32 s15, s9, 0
	s_add_u32 s16, s8, 0x3a800500
	s_addc_u32 s17, s9, 0
	s_add_u32 s18, s8, 0x3a800600
	s_addc_u32 s19, s9, 0
	s_add_u32 s40, s8, 0x3a800700
	s_addc_u32 s41, s9, 0
	s_add_u32 s42, s8, 0x3a800800
	s_addc_u32 s43, s9, 0
	s_add_u32 s44, s8, 0x3a800900
	s_addc_u32 s45, s9, 0
	s_add_u32 s50, s8, 0x3a800a00
	s_addc_u32 s51, s9, 0
	s_add_u32 s52, s8, 0x3a800b00
	s_addc_u32 s53, s9, 0
	s_add_u32 s54, s8, 0x3a800c00
	s_addc_u32 s55, s9, 0
	s_add_u32 s60, s8, 0x3a800d00
	s_addc_u32 s61, s9, 0
	s_add_u32 s46, s8, 0x3a800e00
	s_addc_u32 s47, s9, 0
	s_add_u32 s94, s8, 0x3a800f00
	s_addc_u32 s95, s9, 0
	s_add_u32 s92, s8, 0x3a801000
	s_addc_u32 s93, s9, 0
	s_add_u32 s36, s8, 0x3a801100
	s_addc_u32 s37, s9, 0
	s_add_u32 s56, s8, 0x3a801200
	s_addc_u32 s57, s9, 0
	s_add_u32 s58, s8, 0x3a801300
	s_addc_u32 s59, s9, 0
	s_mov_b32 s4, 1
	s_branch .LBB0_831
